# retention: 2 barriers per chunk - next chunk staged into LDS during step B (V double-buffered), copy/prefetch at chunk end
# speedup vs baseline: 1.0048x; 1.0048x over previous
; #define LAS __attribute__((address_space(3)))
; __device__ __forceinline__ void ret_mfma(const Params& P, LAS unsigned char* lds, int wave) {
;     ...
;         const float gam = 1.f - exp2f(-5.f - (float)hh), lg = log2f(gam), g64 = exp2f(lg * 64.f);
;         for (int i = t; i < 33792 / 16; i += NTHREADS) *(LAS u32x4*)(lds + ST_OFF + i * 16) = (u32x4){0u, 0u, 0u, 0u};
;         f32x16 st[2];
; #pragma unroll
;         for (int a = 0; a < 2; ++a)
; #pragma unroll
;             for (int i = 0; i < 16; ++i) st[a][i] = 0.f;
;         const size_t rb = (size_t)b * SEQ;
;         float dec[16];
;         { const int mblk = (wave & 3) >> 1, nblk = wave & 1, n = nblk * 32 + q32;
; #pragma unroll
;           for (int i = 0; i < 16; ++i) { const int mm = mblk * 32 + 8 * (i >> 2) + 4 * hf + (i & 3); const int dist = n > mm ? n - mm : mm - n;
;               dec[i] = wave < 4 ? __builtin_amdgcn_exp2f(lg * (float)(dist - (63 - mm))) : __builtin_amdgcn_exp2f(lg * (float)(n + 1)); } }
;         u32x4 pq[4], pkk[4], pvv;
;         const int vr = t >> 3, vc = t & 7;
; #pragma unroll
;         for (int i = 0; i < 4; ++i) { const int id = t + 512 * i, r = id >> 5, ch = id & 31;
;             pq[i] = *(const u32x4*)(QK + (rb + r) * 2048 + hh * 256 + ch * 8); pkk[i] = *(const u32x4*)(QK + (rb + r) * 2048 + 1024 + hh * 256 + ch * 8); }
;         pvv = *(const u32x4*)(V + (rb + vr) * 2048 + hh * 512 + slice * 64 + vc * 8);
; #pragma unroll 1
;         for (int c = 0; c < 64; ++c) {
; #pragma unroll
;             for (int i = 0; i < 4; ++i) { const int id = t + 512 * i, r = id >> 5, ch = id & 31;
;                 *(LAS u32x4*)(lds + Q_OFF + r * QP + ch * 16) = pq[i]; *(LAS u32x4*)(lds + K_OFF + r * QP + ch * 16) = pkk[i]; }
;             *(LAS u32x4*)(lds + V_OFF + vr * VP + vc * 16) = pvv;
;             __syncthreads();
;             if (c + 1 < 64) { const size_t r1 = rb + (size_t)(c + 1) * 64;
; #pragma unroll
;                 for (int i = 0; i < 4; ++i) { const int id = t + 512 * i, r = id >> 5, ch = id & 31;
;                     pq[i] = *(const u32x4*)(QK + (r1 + r) * 2048 + hh * 256 + ch * 8); pkk[i] = *(const u32x4*)(QK + (r1 + r) * 2048 + 1024 + hh * 256 + ch * 8); }
;                 pvv = *(const u32x4*)(V + (r1 + vr) * 2048 + hh * 512 + slice * 64 + vc * 8); }
.LBB0_252:
	s_or_b64 exec, exec, s[8:9]
	s_ashr_i32 s9, s28, 6
	s_and_b32 s23, s9, 3
	v_cvt_f32_ubyte0_e32 v0, s23
	v_sub_f32_e32 v0, 0xc0a00000, v0
	v_cmp_gt_f32_e32 vcc, s25, v0
	s_lshl_b32 s8, s28, 2
	s_and_b32 s8, s8, 28
	v_cndmask_b32_e32 v1, 0, v182, vcc
	v_add_f32_e32 v0, v0, v1
	s_add_i32 s8, s8, s9
	v_exp_f32_e32 v0, v0
	s_bfe_u32 s22, s28, 0x30003
	s_ashr_i32 s8, s8, 2
	s_and_b64 s[18:19], vcc, exec
	s_cselect_b32 s9, 0xffffffc0, 0
	v_ldexp_f32 v0, v0, s9
	v_sub_f32_e32 v0, 1.0, v0
	v_cmp_gt_f32_e32 vcc, s26, v0
	s_and_b64 s[18:19], vcc, exec
	s_cselect_b32 s9, 32, 0
	v_ldexp_f32 v0, v0, s9
	v_log_f32_e32 v2, v0
	v_cndmask_b32_e32 v1, 0, v183, vcc
	s_mov_b32 s21, s15
	v_mov_b32_e32 v103, v91
	v_sub_f32_e32 v1, v2, v1
	v_mul_f32_e32 v2, 0x42800000, v1
	v_cmp_gt_f32_e32 vcc, s25, v2
	s_and_b64 s[18:19], vcc, exec
	s_cselect_b32 s9, 0xffffffc0, 0
	v_cndmask_b32_e32 v2, 0, v182, vcc
	v_fmac_f32_e32 v2, 0x42800000, v1
	v_exp_f32_e32 v2, v2
	v_mul_f32_e32 v3, v1, v85
	v_mul_f32_e32 v4, v1, v152
	v_exp_f32_e32 v3, v3
	v_ldexp_f32 v106, v2, s9
	v_mul_f32_e32 v2, v1, v153
	v_exp_f32_e32 v105, v2
	v_mul_f32_e32 v2, v1, v154
	v_exp_f32_e32 v110, v2
	v_mul_f32_e32 v2, v1, v155
	v_exp_f32_e32 v111, v2
	v_mul_f32_e32 v2, v1, v156
	v_exp_f32_e32 v104, v4
	v_exp_f32_e32 v112, v2
	v_mul_f32_e32 v2, v1, v157
	v_exp_f32_e32 v113, v2
	v_mul_f32_e32 v2, v1, v158
	s_ashr_i32 s9, s8, 31
	v_exp_f32_e32 v114, v2
	v_mul_f32_e32 v2, v1, v159
	v_exp_f32_e32 v115, v2
	v_mul_f32_e32 v2, v1, v160
	s_lshl_b64 s[18:19], s[8:9], 12
	v_cndmask_b32_e64 v108, v3, v104, s[4:5]
	v_exp_f32_e32 v116, v2
	v_lshl_add_u64 v[2:3], s[18:19], 0, v[92:93]
	v_lshlrev_b64 v[2:3], 12, v[2:3]
	v_lshl_add_u64 v[2:3], s[44:45], 0, v[2:3]
	s_lshl_b32 s14, s23, 9
	v_lshl_add_u64 v[2:3], v[2:3], 0, s[14:15]
	v_lshl_add_u64 v[2:3], v[2:3], 0, v[90:91]
	s_waitcnt vmcnt(0)
	flat_load_dwordx4 v[48:51], v[2:3]
	flat_load_dwordx4 v[52:55], v[2:3] offset:2048
	v_lshl_add_u64 v[2:3], s[18:19], 0, v[94:95]
	v_lshlrev_b64 v[2:3], 12, v[2:3]
	v_lshl_add_u64 v[2:3], s[44:45], 0, v[2:3]
	v_lshl_add_u64 v[2:3], v[2:3], 0, s[14:15]
	v_lshl_add_u64 v[2:3], v[2:3], 0, v[90:91]
	flat_load_dwordx4 v[56:59], v[2:3]
	flat_load_dwordx4 v[60:63], v[2:3] offset:2048
	v_lshl_add_u64 v[2:3], s[18:19], 0, v[96:97]
	v_lshlrev_b64 v[2:3], 12, v[2:3]
	v_lshl_add_u64 v[2:3], s[44:45], 0, v[2:3]
	v_lshl_add_u64 v[2:3], v[2:3], 0, s[14:15]
	v_lshl_add_u64 v[2:3], v[2:3], 0, v[90:91]
	flat_load_dwordx4 v[64:67], v[2:3]
	flat_load_dwordx4 v[68:71], v[2:3] offset:2048
	v_lshl_add_u64 v[2:3], s[18:19], 0, v[98:99]
	v_lshlrev_b64 v[2:3], 12, v[2:3]
	v_lshl_add_u64 v[2:3], s[44:45], 0, v[2:3]
	v_lshl_add_u64 v[2:3], v[2:3], 0, s[14:15]
	v_lshl_add_u64 v[2:3], v[2:3], 0, v[90:91]
	flat_load_dwordx4 v[72:75], v[2:3]
	flat_load_dwordx4 v[76:79], v[2:3] offset:2048
	v_lshl_add_u64 v[2:3], s[18:19], 0, v[88:89]
	v_lshlrev_b64 v[2:3], 12, v[2:3]
	v_lshl_add_u64 v[2:3], s[36:37], 0, v[2:3]
	s_lshl_b32 s8, s23, 10
	s_mov_b32 s9, s15
	v_lshl_add_u64 v[2:3], v[2:3], 0, s[8:9]
	s_lshl_b32 s20, s22, 7
	v_lshl_add_u64 v[2:3], v[2:3], 0, s[20:21]
	v_lshl_add_u64 v[2:3], v[2:3], 0, v[102:103]
	flat_load_dwordx4 v[80:83], v[2:3]
	s_add_u32 s8, s36, s8
	s_addc_u32 s9, s37, 0
	s_add_u32 s8, s8, s20
	v_mul_f32_e32 v2, v1, v161
	s_addc_u32 s9, s9, 0
	s_lshl_b32 s20, s23, 6
	v_exp_f32_e32 v117, v2
	v_mul_f32_e32 v2, v1, v162
	s_add_u32 s20, s60, s20
	v_exp_f32_e32 v118, v2
	v_mul_f32_e32 v2, v1, v163
	s_addc_u32 s21, s61, 0
	s_lshl_b32 s22, s22, 3
	v_exp_f32_e32 v119, v2
	v_mul_f32_e32 v2, v1, v164
	s_add_u32 s20, s20, s22
	v_exp_f32_e32 v120, v2
	v_mul_f32_e32 v2, v1, v165
	s_addc_u32 s21, s21, 0
	v_exp_f32_e32 v121, v2
	v_mul_f32_e32 v2, v1, v166
	v_mul_f32_e32 v1, v1, v167
	s_add_u32 s20, s20, s16
	v_exp_f32_e32 v122, v2
	v_exp_f32_e32 v123, v1
	s_addc_u32 s21, s21, s17
	v_lshl_add_u64 v[124:125], s[8:9], 0, v[102:103]
	s_add_u32 s8, s8, s27
	v_mov_b32_e32 v0, 0
	s_addc_u32 s9, s9, 0
	s_mov_b32 s29, 0
	v_mov_b32_e32 v126, v106
	v_mov_b32_e32 v127, v106
	v_lshl_add_u64 v[128:129], v[86:87], 1, s[8:9]
	v_mov_b32_e32 v109, v108
	v_lshl_add_u64 v[144:145], v[100:101], 0, s[14:15]
	v_mov_b32_e32 v1, v0
	v_mov_b32_e32 v2, v0
	v_mov_b32_e32 v3, v0
	v_mov_b32_e32 v4, v0
	v_mov_b32_e32 v5, v0
	v_mov_b32_e32 v6, v0
	v_mov_b32_e32 v7, v0
	v_mov_b32_e32 v8, v0
	v_mov_b32_e32 v9, v0
	v_mov_b32_e32 v10, v0
	v_mov_b32_e32 v11, v0
	v_mov_b32_e32 v12, v0
	v_mov_b32_e32 v13, v0
	v_mov_b32_e32 v14, v0
	v_mov_b32_e32 v15, v0
	v_mov_b32_e32 v16, v0
	v_mov_b32_e32 v17, v0
	v_mov_b32_e32 v18, v0
	v_mov_b32_e32 v19, v0
	v_mov_b32_e32 v20, v0
	v_mov_b32_e32 v21, v0
	v_mov_b32_e32 v22, v0
	v_mov_b32_e32 v23, v0
	v_mov_b32_e32 v24, v0
	v_mov_b32_e32 v25, v0
	v_mov_b32_e32 v26, v0
	v_mov_b32_e32 v27, v0
	v_mov_b32_e32 v28, v0
	v_mov_b32_e32 v29, v0
	v_mov_b32_e32 v30, v0
	v_mov_b32_e32 v31, v0
	s_add_u32 s8, s18, 64
	s_addc_u32 s9, s19, 0
	v_lshl_add_u64 v[32:33], s[8:9], 0, v[92:93]
	v_lshlrev_b64 v[32:33], 12, v[32:33]
	v_lshl_add_u64 v[32:33], v[144:145], 0, v[32:33]
	global_load_dwordx4 v[226:229], v[32:33], off
	global_load_dwordx4 v[230:233], v[32:33], off offset:2048
	v_lshl_add_u64 v[32:33], s[8:9], 0, v[94:95]
	v_lshlrev_b64 v[32:33], 12, v[32:33]
	v_lshl_add_u64 v[32:33], v[144:145], 0, v[32:33]
	global_load_dwordx4 v[234:237], v[32:33], off
	global_load_dwordx4 v[238:241], v[32:33], off offset:2048
	v_lshl_add_u64 v[32:33], s[8:9], 0, v[96:97]
	v_lshlrev_b64 v[32:33], 12, v[32:33]
	v_lshl_add_u64 v[32:33], v[144:145], 0, v[32:33]
	global_load_dwordx4 v[246:249], v[32:33], off
	global_load_dwordx4 v[250:253], v[32:33], off offset:2048
	v_lshl_add_u64 v[32:33], s[8:9], 0, v[98:99]
	v_lshlrev_b64 v[32:33], 12, v[32:33]
	v_lshl_add_u64 v[32:33], v[144:145], 0, v[32:33]
	global_load_dwordx4 v[206:209], v[32:33], off
	global_load_dwordx4 v[130:133], v[32:33], off offset:2048
	v_lshl_add_u64 v[32:33], s[8:9], 0, v[88:89]
	v_lshlrev_b64 v[32:33], 12, v[32:33]
	v_lshl_add_u64 v[32:33], v[124:125], 0, v[32:33]
	global_load_dwordx4 v[134:137], v[32:33], off
	s_waitcnt vmcnt(0)
; #define LAS __attribute__((address_space(3)))
; __device__ __forceinline__ void ret_mfma(const Params& P, LAS unsigned char* lds, int wave) {
;     ...
;             for (int i = 0; i < 4; ++i) { const int id = t + 512 * i, r = id >> 5, ch = id & 31;
;                 *(LAS u32x4*)(lds + Q_OFF + r * QP + ch * 16) = pq[i]; *(LAS u32x4*)(lds + K_OFF + r * QP + ch * 16) = pkk[i]; }
;             *(LAS u32x4*)(lds + V_OFF + vr * VP + vc * 16) = pvv;
;             __syncthreads();
;             if (c + 1 < 64) { const size_t r1 = rb + (size_t)(c + 1) * 64;
; #pragma unroll
;                 for (int i = 0; i < 4; ++i) { const int id = t + 512 * i, r = id >> 5, ch = id & 31;
;                     pq[i] = *(const u32x4*)(QK + (r1 + r) * 2048 + hh * 256 + ch * 8); pkk[i] = *(const u32x4*)(QK + (r1 + r) * 2048 + 1024 + hh * 256 + ch * 8); }
;                 pvv = *(const u32x4*)(V + (r1 + vr) * 2048 + hh * 512 + slice * 64 + vc * 8); }
	ds_write_b128 v173, v[48:51]
	ds_write_b128 v173, v[52:55] offset:33792
	ds_write_b128 v174, v[56:59]
	ds_write_b128 v174, v[60:63] offset:33792
	ds_write_b128 v175, v[64:67]
	ds_write_b128 v175, v[68:71] offset:33792
	ds_write_b128 v176, v[72:75]
	ds_write_b128 v176, v[76:79] offset:33792
	ds_write_b128 v177, v[80:83]
	s_waitcnt lgkmcnt(0)
	v_mov_b64_e32 v[48:49], v[226:227]
	v_mov_b64_e32 v[50:51], v[228:229]
	v_mov_b64_e32 v[52:53], v[230:231]
	v_mov_b64_e32 v[54:55], v[232:233]
	v_mov_b64_e32 v[56:57], v[234:235]
	v_mov_b64_e32 v[58:59], v[236:237]
	v_mov_b64_e32 v[60:61], v[238:239]
	v_mov_b64_e32 v[62:63], v[240:241]
	v_mov_b64_e32 v[64:65], v[246:247]
	v_mov_b64_e32 v[66:67], v[248:249]
	v_mov_b64_e32 v[68:69], v[250:251]
	v_mov_b64_e32 v[70:71], v[252:253]
	v_mov_b64_e32 v[72:73], v[206:207]
	v_mov_b64_e32 v[74:75], v[208:209]
	v_mov_b64_e32 v[76:77], v[130:131]
	v_mov_b64_e32 v[78:79], v[132:133]
	v_mov_b64_e32 v[80:81], v[134:135]
	v_mov_b64_e32 v[82:83], v[136:137]
	s_add_u32 s8, s18, 0x80
	s_addc_u32 s9, s19, 0
	v_lshl_add_u64 v[32:33], s[8:9], 0, v[92:93]
	v_lshlrev_b64 v[32:33], 12, v[32:33]
	v_lshl_add_u64 v[32:33], v[144:145], 0, v[32:33]
	global_load_dwordx4 v[226:229], v[32:33], off
	global_load_dwordx4 v[230:233], v[32:33], off offset:2048
	v_lshl_add_u64 v[32:33], s[8:9], 0, v[94:95]
	v_lshlrev_b64 v[32:33], 12, v[32:33]
	v_lshl_add_u64 v[32:33], v[144:145], 0, v[32:33]
	global_load_dwordx4 v[234:237], v[32:33], off
	global_load_dwordx4 v[238:241], v[32:33], off offset:2048
	v_lshl_add_u64 v[32:33], s[8:9], 0, v[96:97]
	v_lshlrev_b64 v[32:33], 12, v[32:33]
	v_lshl_add_u64 v[32:33], v[144:145], 0, v[32:33]
	global_load_dwordx4 v[246:249], v[32:33], off
	global_load_dwordx4 v[250:253], v[32:33], off offset:2048
	v_lshl_add_u64 v[32:33], s[8:9], 0, v[98:99]
	v_lshlrev_b64 v[32:33], 12, v[32:33]
	v_lshl_add_u64 v[32:33], v[144:145], 0, v[32:33]
	global_load_dwordx4 v[206:209], v[32:33], off
	global_load_dwordx4 v[130:133], v[32:33], off offset:2048
	v_lshl_add_u64 v[32:33], s[8:9], 0, v[88:89]
	v_lshlrev_b64 v[32:33], 12, v[32:33]
	v_lshl_add_u64 v[32:33], v[124:125], 0, v[32:33]
	global_load_dwordx4 v[134:137], v[32:33], off
	s_mov_b32 s30, 0
	s_barrier
	s_branch .LBB0_255

; __device__ __forceinline__ void ret_mfma(const Params& P, LAS unsigned char* lds, int wave) {
;     ...
;             __syncthreads();
;             if (c + 1 < 64) { const size_t r1 = rb + (size_t)(c + 1) * 64;
; #pragma unroll
;                 for (int i = 0; i < 4; ++i) { const int id = t + 512 * i, r = id >> 5, ch = id & 31;
;                     pq[i] = *(const u32x4*)(QK + (r1 + r) * 2048 + hh * 256 + ch * 8); pkk[i] = *(const u32x4*)(QK + (r1 + r) * 2048 + 1024 + hh * 256 + ch * 8); }
;                 pvv = *(const u32x4*)(V + (r1 + vr) * 2048 + hh * 512 + slice * 64 + vc * 8); }
;             const size_t r0 = rb + (size_t)c * 64;
.LBB0_254:
	s_waitcnt lgkmcnt(0)
	s_andn2_b64 vcc, exec, s[10:11]
	s_cbranch_vccnz .Lret_wait_lo
	s_waitcnt vmcnt(5)
	s_branch .Lret_wait_done

; __device__ __forceinline__ void ret_mfma(const Params& P, LAS unsigned char* lds, int wave) {
;     ...
;             if (c + 1 < 64) { const size_t r1 = rb + (size_t)(c + 1) * 64;
; #pragma unroll
;                 for (int i = 0; i < 4; ++i) { const int id = t + 512 * i, r = id >> 5, ch = id & 31;
;                     pq[i] = *(const u32x4*)(QK + (r1 + r) * 2048 + hh * 256 + ch * 8); pkk[i] = *(const u32x4*)(QK + (r1 + r) * 2048 + 1024 + hh * 256 + ch * 8); }
;                 pvv = *(const u32x4*)(V + (r1 + vr) * 2048 + hh * 512 + slice * 64 + vc * 8); }
.Lret_wait_done:
	v_mov_b64_e32 v[48:49], v[226:227]
	v_mov_b64_e32 v[50:51], v[228:229]
	v_mov_b64_e32 v[52:53], v[230:231]
	v_mov_b64_e32 v[54:55], v[232:233]
	v_mov_b64_e32 v[56:57], v[234:235]
	v_mov_b64_e32 v[58:59], v[236:237]
	v_mov_b64_e32 v[60:61], v[238:239]
	v_mov_b64_e32 v[62:63], v[240:241]
	v_mov_b64_e32 v[64:65], v[246:247]
	v_mov_b64_e32 v[66:67], v[248:249]
	v_mov_b64_e32 v[68:69], v[250:251]
	v_mov_b64_e32 v[70:71], v[252:253]
	v_mov_b64_e32 v[72:73], v[206:207]
	v_mov_b64_e32 v[74:75], v[208:209]
	v_mov_b64_e32 v[76:77], v[130:131]
	v_mov_b64_e32 v[78:79], v[132:133]
	v_mov_b64_e32 v[80:81], v[134:135]
	v_mov_b64_e32 v[82:83], v[136:137]
	s_xor_b32 s30, s30, 0x3000
	s_cmp_lt_u32 s14, 62
	s_cbranch_scc0 .Lret_noload
	s_lshl_b32 s8, s14, 6
	s_add_i32 s8, s8, 0x80
	s_add_u32 s8, s18, s8
	s_addc_u32 s9, s19, 0
	v_lshl_add_u64 v[32:33], s[8:9], 0, v[92:93]
	v_lshlrev_b64 v[32:33], 12, v[32:33]
	v_lshl_add_u64 v[32:33], v[144:145], 0, v[32:33]
	global_load_dwordx4 v[226:229], v[32:33], off
	global_load_dwordx4 v[230:233], v[32:33], off offset:2048
	v_lshl_add_u64 v[32:33], s[8:9], 0, v[94:95]
	v_lshlrev_b64 v[32:33], 12, v[32:33]
	v_lshl_add_u64 v[32:33], v[144:145], 0, v[32:33]
	global_load_dwordx4 v[234:237], v[32:33], off
	global_load_dwordx4 v[238:241], v[32:33], off offset:2048
	v_lshl_add_u64 v[32:33], s[8:9], 0, v[96:97]
	v_lshlrev_b64 v[32:33], 12, v[32:33]
	v_lshl_add_u64 v[32:33], v[144:145], 0, v[32:33]
	global_load_dwordx4 v[246:249], v[32:33], off
	global_load_dwordx4 v[250:253], v[32:33], off offset:2048
	v_lshl_add_u64 v[32:33], s[8:9], 0, v[98:99]
	v_lshlrev_b64 v[32:33], 12, v[32:33]
	v_lshl_add_u64 v[32:33], v[144:145], 0, v[32:33]
	global_load_dwordx4 v[206:209], v[32:33], off
	global_load_dwordx4 v[130:133], v[32:33], off offset:2048
	v_lshl_add_u64 v[32:33], s[8:9], 0, v[88:89]
	v_lshlrev_b64 v[32:33], 12, v[32:33]
	v_lshl_add_u64 v[32:33], v[124:125], 0, v[32:33]
	global_load_dwordx4 v[134:137], v[32:33], off

; #define LAS __attribute__((address_space(3)))
; __device__ __forceinline__ void ret_mfma(const Params& P, LAS unsigned char* lds, int wave) {
;     ...
;             if (wave < 4) {
;                 const int mblk = wave >> 1, nblk = wave & 1, n = nblk * 32 + q32;
; #pragma unroll 4
;                 for (int ks = 0; ks < 16; ++ks) {
;                     const bf16x8 a = *(const LAS bf16x8*)(lds + K_OFF + (mblk * 32 + q32) * QP + ks * 32 + hf * 16);
;                     const bf16x8 bq = *(const LAS bf16x8*)(lds + Q_OFF + n * QP + ks * 32 + hf * 16);
;                     acc = __builtin_amdgcn_mfma_f32_32x32x16_bf16(a, bq, acc, 0, 0, 0);
;                 }
; #pragma unroll
;                 for (int i = 0; i < 16; ++i) acc[i] *= dec[i];
; #pragma unroll
;                 for (int j = 0; j < 4; ++j) { u32x2 w; w.x = cvt_pk_bf16(acc[4 * j], acc[4 * j + 1]); w.y = cvt_pk_bf16(acc[4 * j + 2], acc[4 * j + 3]);
;                     *(LAS u32x2*)(lds + S_OFF + n * SP + (mblk * 32 + 8 * j + 4 * hf) * 2) = w; }
;             } else {
;                 const int w4 = wave - 4, dvblk = w4 >> 1, nblk = w4 & 1, n = nblk * 32 + q32;
; #pragma unroll 4
;                 for (int ks = 0; ks < 16; ++ks) {
;                     const bf16x8 a = *(const LAS bf16x8*)(lds + ST_OFF + (dvblk * 32 + q32) * QP + ks * 32 + hf * 16);
;                     const bf16x8 bq = *(const LAS bf16x8*)(lds + Q_OFF + n * QP + ks * 32 + hf * 16);
;                     acc = __builtin_amdgcn_mfma_f32_32x32x16_bf16(a, bq, acc, 0, 0, 0);
;                 }
;                 acc = acc * dec[0];
;             }
;             __syncthreads();
;             {
; #pragma unroll
;                 for (int a = 0; a < 2; ++a) st[a] = st[a] * g64;
; #pragma unroll
;                 for (int ks = 0; ks < 4; ++ks) {
;                     bf16x8 av[2], bk;
; #pragma unroll
;                     for (int vb = 0; vb < 2; ++vb) { const LAS unsigned char* p = lds + V_OFF + (16 * ks + trrow) * VP + vb * 64 + trcol; av[vb] = tr_pair(p, p + 4 * VP); }
;                     { const LAS unsigned char* p = lds + K_OFF + (16 * ks + trrow) * QP + wave * 64 + trcol; bk = tr_pair(p, p + 4 * QP); }
; #pragma unroll
;                     for (int vb = 0; vb < 2; ++vb) st[vb] = __builtin_amdgcn_mfma_f32_32x32x16_bf16(av[vb], bk, st[vb], 0, 0, 0);
;                 }
.LBB0_257:
	v_add3_u32 v103, v148, v168, s30
	ds_read_b64_tr_b16 v[190:191], v103
	ds_read_b64_tr_b16 v[192:193], v103 offset:768
	ds_read_b64_tr_b16 v[198:199], v179 offset:33792
	ds_read_b64_tr_b16 v[200:201], v179 offset:35904
	ds_read_b64_tr_b16 v[194:195], v103 offset:64
	ds_read_b64_tr_b16 v[196:197], v103 offset:832
	ds_read_b64_tr_b16 v[202:203], v103 offset:3072
	ds_read_b64_tr_b16 v[204:205], v103 offset:3840
	ds_read_b64_tr_b16 v[214:215], v179 offset:42240
	ds_read_b64_tr_b16 v[216:217], v179 offset:44352
	ds_read_b64_tr_b16 v[210:211], v103 offset:3136
	ds_read_b64_tr_b16 v[212:213], v103 offset:3904
	v_pk_mul_f32 v[0:1], v[126:127], v[0:1]
	v_pk_mul_f32 v[2:3], v[126:127], v[2:3]
	v_pk_mul_f32 v[4:5], v[126:127], v[4:5]
	v_pk_mul_f32 v[6:7], v[126:127], v[6:7]
	v_pk_mul_f32 v[8:9], v[126:127], v[8:9]
	v_pk_mul_f32 v[10:11], v[126:127], v[10:11]
	v_pk_mul_f32 v[12:13], v[126:127], v[12:13]
	v_pk_mul_f32 v[14:15], v[126:127], v[14:15]
	v_pk_mul_f32 v[16:17], v[126:127], v[16:17]
	v_pk_mul_f32 v[18:19], v[126:127], v[18:19]
	v_pk_mul_f32 v[20:21], v[126:127], v[20:21]
	v_pk_mul_f32 v[22:23], v[126:127], v[22:23]
	v_pk_mul_f32 v[24:25], v[126:127], v[24:25]
	v_pk_mul_f32 v[26:27], v[126:127], v[26:27]
	v_pk_mul_f32 v[28:29], v[126:127], v[28:29]
	v_pk_mul_f32 v[30:31], v[126:127], v[30:31]
	s_waitcnt lgkmcnt(6)
	v_mfma_f32_32x32x16_bf16 v[0:15], v[198:201], v[190:193], v[0:15]
	v_mfma_f32_32x32x16_bf16 v[16:31], v[198:201], v[194:197], v[16:31]
	ds_read_b64_tr_b16 v[190:191], v103 offset:6144
	ds_read_b64_tr_b16 v[192:193], v103 offset:6912
	ds_read_b64_tr_b16 v[198:199], v179 offset:50688
	ds_read_b64_tr_b16 v[200:201], v179 offset:52800
	ds_read_b64_tr_b16 v[194:195], v103 offset:6208
	ds_read_b64_tr_b16 v[196:197], v103 offset:6976
	s_waitcnt lgkmcnt(6)
	v_mfma_f32_32x32x16_bf16 v[0:15], v[214:217], v[202:205], v[0:15]
	v_mfma_f32_32x32x16_bf16 v[16:31], v[214:217], v[210:213], v[16:31]
	ds_read_b64_tr_b16 v[202:203], v103 offset:9216
	ds_read_b64_tr_b16 v[204:205], v103 offset:9984
	ds_read_b64_tr_b16 v[214:215], v179 offset:59136
	ds_read_b64_tr_b16 v[216:217], v179 offset:61248
	ds_read_b64_tr_b16 v[210:211], v103 offset:9280
	ds_read_b64_tr_b16 v[212:213], v103 offset:10048
	s_waitcnt lgkmcnt(6)
	v_mfma_f32_32x32x16_bf16 v[0:15], v[198:201], v[190:193], v[0:15]
	v_mfma_f32_32x32x16_bf16 v[16:31], v[198:201], v[194:197], v[16:31]
	s_waitcnt lgkmcnt(0)
	v_mfma_f32_32x32x16_bf16 v[0:15], v[214:217], v[202:205], v[0:15]
	v_mfma_f32_32x32x16_bf16 v[16:31], v[214:217], v[210:213], v[16:31]
	v_cndmask_b32_e64 v32, 0, 1, s[10:11]
	v_cmp_ne_u32_e64 s[8:9], 1, v32
	s_andn2_b64 vcc, exec, s[10:11]
	s_mov_b64 s[22:23], -1
	s_cbranch_vccnz .LBB0_261
	ds_read_b128 v[190:193], v171
	ds_read_b128 v[194:197], v150
	ds_read_b128 v[198:201], v171 offset:32
	ds_read_b128 v[202:205], v150 offset:32
	ds_read_b128 v[210:213], v171 offset:64
	ds_read_b128 v[214:217], v150 offset:64
	ds_read_b128 v[218:221], v171 offset:96
	ds_read_b128 v[222:225], v150 offset:96
	s_waitcnt lgkmcnt(6)
	v_mfma_f32_32x32x16_bf16 v[32:47], v[190:193], v[194:197], 0
	ds_read_b128 v[190:193], v171 offset:128
	ds_read_b128 v[194:197], v150 offset:128
	s_waitcnt lgkmcnt(6)
	v_mfma_f32_32x32x16_bf16 v[32:47], v[198:201], v[202:205], v[32:47]
	ds_read_b128 v[198:201], v171 offset:160
	ds_read_b128 v[202:205], v150 offset:160
	s_waitcnt lgkmcnt(6)
	v_mfma_f32_32x32x16_bf16 v[32:47], v[210:213], v[214:217], v[32:47]
	ds_read_b128 v[210:213], v171 offset:192
	ds_read_b128 v[214:217], v150 offset:192
	s_waitcnt lgkmcnt(6)
	v_mfma_f32_32x32x16_bf16 v[32:47], v[218:221], v[222:225], v[32:47]
	ds_read_b128 v[218:221], v171 offset:224
	ds_read_b128 v[222:225], v150 offset:224
	s_waitcnt lgkmcnt(6)
	v_mfma_f32_32x32x16_bf16 v[32:47], v[190:193], v[194:197], v[32:47]
	ds_read_b128 v[190:193], v171 offset:256
	ds_read_b128 v[194:197], v150 offset:256
	s_waitcnt lgkmcnt(6)
	v_mfma_f32_32x32x16_bf16 v[32:47], v[198:201], v[202:205], v[32:47]
	ds_read_b128 v[198:201], v171 offset:288
	ds_read_b128 v[202:205], v150 offset:288
	s_waitcnt lgkmcnt(6)
	v_mfma_f32_32x32x16_bf16 v[32:47], v[210:213], v[214:217], v[32:47]
	ds_read_b128 v[210:213], v171 offset:320
	ds_read_b128 v[214:217], v150 offset:320
	s_waitcnt lgkmcnt(6)
	v_mfma_f32_32x32x16_bf16 v[32:47], v[218:221], v[222:225], v[32:47]
	ds_read_b128 v[218:221], v171 offset:352
	ds_read_b128 v[222:225], v150 offset:352
	s_waitcnt lgkmcnt(6)
	v_mfma_f32_32x32x16_bf16 v[32:47], v[190:193], v[194:197], v[32:47]
	ds_read_b128 v[190:193], v171 offset:384
	ds_read_b128 v[194:197], v150 offset:384
	s_waitcnt lgkmcnt(6)
	v_mfma_f32_32x32x16_bf16 v[32:47], v[198:201], v[202:205], v[32:47]
	ds_read_b128 v[198:201], v171 offset:416
	ds_read_b128 v[202:205], v150 offset:416
	s_waitcnt lgkmcnt(6)
	v_mfma_f32_32x32x16_bf16 v[32:47], v[210:213], v[214:217], v[32:47]
	ds_read_b128 v[210:213], v171 offset:448
	ds_read_b128 v[214:217], v150 offset:448
	s_waitcnt lgkmcnt(6)
	v_mfma_f32_32x32x16_bf16 v[32:47], v[218:221], v[222:225], v[32:47]
	ds_read_b128 v[218:221], v171 offset:480
	ds_read_b128 v[222:225], v150 offset:480
	s_waitcnt lgkmcnt(6)
	v_mfma_f32_32x32x16_bf16 v[32:47], v[190:193], v[194:197], v[32:47]
	s_waitcnt lgkmcnt(4)
	v_mfma_f32_32x32x16_bf16 v[32:47], v[198:201], v[202:205], v[32:47]
	s_waitcnt lgkmcnt(2)
	v_mfma_f32_32x32x16_bf16 v[32:47], v[210:213], v[214:217], v[32:47]
	s_waitcnt lgkmcnt(0)
	v_mfma_f32_32x32x16_bf16 v[32:47], v[218:221], v[222:225], v[32:47]
	s_nop 11
	v_pk_mul_f32 v[46:47], v[108:109], v[46:47]
	v_pk_mul_f32 v[44:45], v[108:109], v[44:45]
	v_pk_mul_f32 v[42:43], v[108:109], v[42:43]
	v_pk_mul_f32 v[40:41], v[108:109], v[40:41]
	v_pk_mul_f32 v[38:39], v[108:109], v[38:39]
	v_pk_mul_f32 v[36:37], v[108:109], v[36:37]
	v_pk_mul_f32 v[34:35], v[108:109], v[34:35]
	v_pk_mul_f32 v[32:33], v[108:109], v[32:33]
	s_mov_b64 s[22:23], 0

; #define LAS __attribute__((address_space(3)))
; __device__ __forceinline__ unsigned cvt_pk_bf16(float lo, float hi) { f32x2 v = {lo, hi}; bf16x2_t b = __builtin_convertvector(v, bf16x2_t); return __builtin_bit_cast(unsigned, b); }
; __device__ __forceinline__ void ret_mfma(const Params& P, LAS unsigned char* lds, int wave) {
;     ...
;             for (int i = 0; i < 4; ++i) { const int id = t + 512 * i, r = id >> 5, ch = id & 31;
;                 *(LAS u32x4*)(lds + Q_OFF + r * QP + ch * 16) = pq[i]; *(LAS u32x4*)(lds + K_OFF + r * QP + ch * 16) = pkk[i]; }
;             *(LAS u32x4*)(lds + V_OFF + vr * VP + vc * 16) = pvv;
;     ...
; #pragma unroll
;                 for (int vb = 0; vb < 2; ++vb)
; #pragma unroll
;                     for (int i = 0; i < 16; ++i) { const int dv = vb * 32 + 8 * (i >> 2) + 4 * hf + (i & 3);
;                         *(LAS bf16_t*)(lds + ST_OFF + dv * QP + (wave * 32 + q32) * 2) = (bf16_t)(cvt_pk_bf16(st[vb][i], 0.f) & 0xffffu); }
;             }
;             if (wave >= 4) {
;                 const int w4 = wave - 4, dvblk = w4 >> 1, nblk = w4 & 1, n = nblk * 32 + q32;
; #pragma unroll
;                 for (int ks = 0; ks < 4; ++ks) {
;                     const LAS unsigned char* p = lds + V_OFF + (16 * ks + trrow) * VP + dvblk * 64 + trcol;
;                     const bf16x8 a = tr_pair(p, p + 4 * VP);
;                     const bf16x8 bs = *(const LAS bf16x8*)(lds + S_OFF + n * SP + (16 * ks + 8 * hf) * 2);
;                     acc = __builtin_amdgcn_mfma_f32_32x32x16_bf16(a, bs, acc, 0, 0, 0);
;                 }
;                 float sq = 0.f;
; #pragma unroll
;                 for (int i = 0; i < 16; ++i) sq += acc[i] * acc[i];
;                 sq += __shfl_xor(sq, 32);
;                 if (hf == 0) rssq[(r0 + n) * 64 + hh * 16 + slice * 2 + dvblk] = sq;
;                 bf16_t* op = V + (r0 + n) * 2048 + hh * 512 + slice * 64 + dvblk * 32 + 4 * hf;
; #pragma unroll
;                 for (int j = 0; j < 4; ++j) { u32x2 w; w.x = cvt_pk_bf16(acc[4 * j], acc[4 * j + 1]); w.y = cvt_pk_bf16(acc[4 * j + 2], acc[4 * j + 3]); *(u32x2*)(op + 8 * j) = w; }
;             }
.LBB0_265:
	s_waitcnt lgkmcnt(0)
	s_barrier
	s_xor_b32 s31, s30, 0x3000
	v_add_u32_e32 v107, s31, v177
	ds_write_b128 v173, v[48:51]
	ds_write_b128 v173, v[52:55] offset:33792
	ds_write_b128 v174, v[56:59]
	ds_write_b128 v174, v[60:63] offset:33792
	ds_write_b128 v175, v[64:67]
	ds_write_b128 v175, v[68:71] offset:33792
	ds_write_b128 v176, v[72:75]
	ds_write_b128 v176, v[76:79] offset:33792
	ds_write_b128 v107, v[80:83]
	s_and_b64 vcc, exec, s[8:9]
	v_cvt_pk_bf16_f32 v218, v0, v1
	v_cvt_pk_bf16_f32 v219, v2, v3
	ds_write_b64 v242, v[218:219]
	v_cvt_pk_bf16_f32 v220, v4, v5
	v_cvt_pk_bf16_f32 v221, v6, v7
	ds_write_b64 v242, v[220:221] offset:16
	v_cvt_pk_bf16_f32 v222, v8, v9
	v_cvt_pk_bf16_f32 v223, v10, v11
	ds_write_b64 v242, v[222:223] offset:32
	v_cvt_pk_bf16_f32 v224, v12, v13
	v_cvt_pk_bf16_f32 v225, v14, v15
	ds_write_b64 v242, v[224:225] offset:48
	v_cvt_pk_bf16_f32 v218, v16, v17
	v_cvt_pk_bf16_f32 v219, v18, v19
	ds_write_b64 v242, v[218:219] offset:16896
	v_cvt_pk_bf16_f32 v220, v20, v21
	v_cvt_pk_bf16_f32 v221, v22, v23
	ds_write_b64 v242, v[220:221] offset:16912
	v_cvt_pk_bf16_f32 v222, v24, v25
	v_cvt_pk_bf16_f32 v223, v26, v27
	ds_write_b64 v242, v[222:223] offset:16928
	v_cvt_pk_bf16_f32 v224, v28, v29
	v_cvt_pk_bf16_f32 v225, v30, v31
	ds_write_b64 v242, v[224:225] offset:16944
	s_cbranch_vccnz .LBB0_254
	v_add_u32_e32 v185, s30, v181
	ds_read_b64_tr_b16 v[190:191], v185
	ds_read_b64_tr_b16 v[192:193], v185 offset:768
	v_add_u32_e32 v103, v151, v149
	ds_read_b128 v[194:197], v103
	ds_read_b64_tr_b16 v[198:199], v185 offset:3072
	ds_read_b64_tr_b16 v[200:201], v185 offset:3840
	ds_read_b128 v[202:205], v103 offset:32
	v_and_b32_e32 v107, 64, v184
	v_add_u32_e32 v107, 64, v107
	s_waitcnt lgkmcnt(0)
	v_mfma_f32_32x32x16_bf16 v[32:47], v[190:193], v[194:197], v[32:47]
	s_lshl_b32 s8, s29, 6
	s_or_b32 s8, s18, s8
	v_or_b32_e32 v146, s8, v84
	v_mfma_f32_32x32x16_bf16 v[32:47], v[198:201], v[202:205], v[32:47]
	ds_read_b64_tr_b16 v[190:191], v185 offset:6144
	ds_read_b64_tr_b16 v[192:193], v185 offset:6912
	ds_read_b128 v[194:197], v103 offset:64
	ds_read_b64_tr_b16 v[198:199], v185 offset:9216
	ds_read_b64_tr_b16 v[200:201], v185 offset:9984
	ds_read_b128 v[202:205], v103 offset:96
	v_xor_b32_e32 v103, 32, v184
	v_cmp_lt_i32_e32 vcc, v103, v107
	s_nop 1
	v_cndmask_b32_e32 v107, v184, v103, vcc
	v_lshlrev_b32_e32 v107, 2, v107
	s_waitcnt lgkmcnt(0)
	v_mfma_f32_32x32x16_bf16 v[32:47], v[190:193], v[194:197], v[32:47]
	v_mfma_f32_32x32x16_bf16 v[32:47], v[198:201], v[202:205], v[32:47]
	s_nop 11
	v_mul_f32_e32 v103, v33, v33
	v_fmac_f32_e32 v103, v32, v32
	v_fmac_f32_e32 v103, v34, v34
	v_fmac_f32_e32 v103, v35, v35
	v_fmac_f32_e32 v103, v36, v36
	v_fmac_f32_e32 v103, v37, v37
	v_fmac_f32_e32 v103, v38, v38
	v_fmac_f32_e32 v103, v39, v39
	v_fmac_f32_e32 v103, v40, v40
	v_fmac_f32_e32 v103, v41, v41
	v_fmac_f32_e32 v103, v42, v42
	v_fmac_f32_e32 v103, v43, v43
	v_fmac_f32_e32 v103, v44, v44
	v_fmac_f32_e32 v103, v45, v45
	v_fmac_f32_e32 v103, v46, v46
	v_fmac_f32_e32 v103, v47, v47
	ds_bpermute_b32 v107, v107, v103
	s_and_saveexec_b64 s[8:9], s[6:7]
	s_xor_b64 s[8:9], exec, s[8:9]
	v_mov_b32_e32 v147, s19
	s_andn2_saveexec_b64 s[8:9], s[8:9]
	s_cbranch_execz .LBB0_253
	v_mov_b32_e32 v147, s19
	v_lshlrev_b64 v[190:191], 8, v[146:147]
	s_waitcnt lgkmcnt(0)
	v_add_f32_e32 v103, v103, v107
	v_lshl_add_u64 v[190:191], s[20:21], 0, v[190:191]
	flat_store_dword v[190:191], v103
	s_branch .LBB0_253
